# weight transposes rewritten: each lane loads an 8x4 f32 block with dwordx4 nt loads, packs with v_cvt_pk_bf16_f32 and stores dwordx4; no LDS staging
# speedup vs baseline: 1.0024x; 1.0024x over previous
; #define LAS __attribute__((address_space(3)))
; #define LDS_WAIT() asm volatile("s_waitcnt lgkmcnt(0)" ::: "memory")
; __device__ __forceinline__ unsigned pk2(float lo, float hi) { return f2bf(lo) | (f2bf(hi) << 16); }
; __device__ __forceinline__ void transpose_item(const float* W, int K, int N, bf16* WT, LAS float* scr, int item, int lane, bool bcu_map = false) {
;     const int nblk = N / 32, kb = item / nblk, nb = item % nblk, k0 = 64 * kb, n0 = 32 * nb;
; #pragma unroll 8
;     for (int i = 0; i < 32; ++i) { const int kk = 2 * i + (lane >> 5); scr[kk * 33 + (lane & 31)] = W[(size_t)(k0 + kk) * N + n0 + (lane & 31)]; }
;     LDS_WAIT(); asm volatile("" ::: "memory");
;     const int c = lane & 7;
; #pragma unroll
;     for (int j = 0; j < 4; ++j) { const int n = (lane >> 3) + 8 * j; const LAS float* s = scr + (8 * c) * 33 + n;
;         v4u o; o.x = pk2(s[0 * 33], s[1 * 33]); o.y = pk2(s[2 * 33], s[3 * 33]); o.z = pk2(s[4 * 33], s[5 * 33]); o.w = pk2(s[6 * 33], s[7 * 33]);
;         const int f_ = (n0 & 2047), row_ = !bcu_map ? n0 : (n0 < 2048 ? n0 : 2048 + (f_ >> 7) * 256 + (n0 >= 4096 ? 128 : 0) + (f_ & 127));
;         *(v4u*)(WT + (size_t)(row_ + n) * K + k0 + 8 * c) = o; }
; __global__ void __launch_bounds__(NWAVES * 64, 2) mega_fwd(Args args) {
;     ...
;         for (int rep = 0; rep < EXP_PRO_REP; ++rep)
;         for (int it = gw; it < NITEMS; it += NGW) {
;             int r = it;
;             if (r < I_IN) { transpose_item(conv_w_in, D, 3 * D, Win_t, scr, r, lane, true); continue; } r -= I_IN;
;             if (r < I_IN) { transpose_item(attn_w_qkv, D, 3 * D, Wqkv_t, scr, r, lane); continue; } r -= I_IN;
;             if (r < I_SQ) { transpose_item(conv_w_out, D, D, Wout_t, scr, r, lane); continue; } r -= I_SQ;
;             if (r < I_SQ) { transpose_item(attn_w_o, D, D, Wo_t, scr, r, lane); continue; } r -= I_SQ;
;             if (r < 2 * I_1) { const int l = r / I_1; transpose_item(mlp_w1 + (size_t)l * D * FF, D, FF, W1_t + (size_t)l * D * FF, scr, r % I_1, lane); continue; } r -= 2 * I_1;
;             { const int l = r / I_2; transpose_item(mlp_w2 + (size_t)l * D * FF, FF, D, W2_t + (size_t)l * D * FF, scr, r % I_2, lane); }
.LBB0_5:
	s_or_b64 exec, exec, s[4:5]
	s_lshl_b32 s34, s56, 3
	s_add_u32 s8, s54, 0x1800000
	s_addc_u32 s9, s55, 0
	s_add_u32 s12, s54, 0x2000000
	s_addc_u32 s13, s55, 0
	s_add_u32 s58, s54, 0x3800000
	s_addc_u32 s59, s55, 0
	s_add_u32 s90, s54, 0x4000000
	s_load_dwordx16 s[36:51], s[0:1], 0x0
	s_load_dwordx16 s[16:31], s[0:1], 0x40
	s_addc_u32 s91, s55, 0
	s_add_u32 s92, s54, 0x8000000
	s_addc_u32 s93, s55, 0
	s_ashr_i32 s0, s14, 6
	s_lshl_b32 s1, s3, 3
	s_add_i32 s14, s0, s1
	v_writelane_b32 v255, s1, 1
	s_cmp_gt_i32 s14, 0xbfff
	v_and_b32_e32 v7, 63, v4
	s_cbranch_scc1 .LBB0_40
	s_waitcnt lgkmcnt(0)
	v_and_b32_e32 v1, 56, v7
	v_and_b32_e32 v2, 7, v7
	v_lshlrev_b32_e32 v3, 2, v2
	v_lshlrev_b32_e32 v5, 1, v1
	s_mov_b32 s33, s14
	s_mov_b32 s15, s33
	s_cmp_lt_u32 s15, 0x1800
	s_cbranch_scc1 .Ltr_a1
	s_sub_u32 s15, s15, 0x1800
	s_cmp_lt_u32 s15, 0x1800
	s_cbranch_scc1 .Ltr_b1
	s_sub_u32 s15, s15, 0x1800
	s_cmp_lt_u32 s15, 0x800
	s_cbranch_scc1 .Ltr_c1
	s_sub_u32 s15, s15, 0x800
	s_cmp_lt_u32 s15, 0x800
	s_cbranch_scc1 .Ltr_d1
	s_sub_u32 s15, s15, 0x800
	s_cmp_lt_u32 s15, 0x4000
	s_cbranch_scc1 .Ltr_e1
	s_sub_u32 s15, s15, 0x4000
	s_lshr_b32 s4, s15, 13
	s_and_b32 s15, s15, 0x1fff
	s_lshl_b32 s63, s4, 26
	s_add_u32 s0, s28, s63
	s_addc_u32 s1, s29, 0
	s_lshl_b32 s63, s4, 25
	s_add_u32 s60, s92, s63
	s_addc_u32 s61, s93, 0
	s_movk_i32 s5, 0x800
	s_movk_i32 s6, 0x2000
	s_mov_b32 s7, 0
	s_lshr_b32 s67, s15, 6
	s_and_b32 s68, s15, 63
	s_branch .Ltr_j1
.Ltr_a1:
	s_mov_b64 s[0:1], s[42:43]
	s_mov_b64 s[60:61], s[54:55]
	s_movk_i32 s5, 0x1800
	s_movk_i32 s6, 0x800
	s_mov_b32 s7, 1
	s_lshr_b32 s67, s15, 6
	s_mul_i32 s67, s67, 171
	s_lshr_b32 s67, s67, 9
	s_mul_i32 s68, s67, 192
	s_sub_u32 s68, s15, s68
	s_branch .Ltr_j1
.Ltr_b1:
	s_mov_b64 s[0:1], s[48:49]
	s_mov_b64 s[60:61], s[12:13]
	s_movk_i32 s5, 0x1800
	s_movk_i32 s6, 0x800
	s_mov_b32 s7, 0
	s_lshr_b32 s67, s15, 6
	s_mul_i32 s67, s67, 171
	s_lshr_b32 s67, s67, 9
	s_mul_i32 s68, s67, 192
	s_sub_u32 s68, s15, s68
	s_branch .Ltr_j1
.Ltr_c1:
	s_mov_b64 s[0:1], s[46:47]
	s_mov_b64 s[60:61], s[8:9]
	s_movk_i32 s5, 0x800
	s_movk_i32 s6, 0x800
	s_mov_b32 s7, 0
	s_lshr_b32 s67, s15, 6
	s_and_b32 s68, s15, 63
	s_branch .Ltr_j1
.Ltr_d1:
	s_mov_b64 s[0:1], s[24:25]
	s_mov_b64 s[60:61], s[58:59]
	s_movk_i32 s5, 0x800
	s_movk_i32 s6, 0x800
	s_mov_b32 s7, 0
	s_lshr_b32 s67, s15, 6
	s_and_b32 s68, s15, 63
	s_branch .Ltr_j1
.Ltr_e1:
	s_lshr_b32 s4, s15, 13
	s_and_b32 s15, s15, 0x1fff
	s_lshl_b32 s63, s4, 26
	s_add_u32 s0, s26, s63
	s_addc_u32 s1, s27, 0
	s_lshl_b32 s63, s4, 25
	s_add_u32 s60, s90, s63
	s_addc_u32 s61, s91, 0
	s_movk_i32 s5, 0x2000
	s_movk_i32 s6, 0x800
	s_mov_b32 s7, 0
	s_lshr_b32 s67, s15, 8
	s_and_b32 s68, s15, 0xff
.Ltr_j1:
	s_lshl_b32 s67, s67, 6
	s_lshl_b32 s68, s68, 5
	s_mul_i32 s63, s67, s5
	s_add_u32 s63, s63, s68
	s_lshl_b32 s63, s63, 2
	s_add_u32 s0, s0, s63
	s_addc_u32 s1, s1, 0
	s_lshl_b32 s3, s5, 2
	s_mov_b32 s69, s68
	s_cmp_eq_u32 s7, 0
	s_cbranch_scc1 .Ltr_r1
	s_cmp_lt_u32 s68, 0x800
	s_cbranch_scc1 .Ltr_r1
	s_and_b32 s70, s68, 0x7ff
	s_lshr_b32 s69, s70, 7
	s_lshl_b32 s69, s69, 8
	s_add_u32 s69, s69, 0x800
	s_and_b32 s70, s70, 0x7f
	s_add_u32 s69, s69, s70
	s_cmp_lt_u32 s68, 0x1000
	s_cbranch_scc1 .Ltr_r1
	s_add_u32 s69, s69, 0x80
.Ltr_r1:
	s_mul_i32 s63, s69, s6
	s_add_u32 s63, s63, s67
	s_lshl_b32 s63, s63, 1
	s_add_u32 s60, s60, s63
	s_addc_u32 s61, s61, 0
	s_lshl_b32 s62, s6, 1
	v_mul_u32_u24_e32 v8, s3, v1
	v_lshl_add_u32 v8, v2, 4, v8
	v_mul_u32_u24_e32 v9, s62, v3
	v_add_u32_e32 v9, v5, v9
	global_load_dwordx4 v[16:19], v8, s[0:1] nt
	v_add_u32_e32 v8, s3, v8
	global_load_dwordx4 v[20:23], v8, s[0:1] nt
	v_add_u32_e32 v8, s3, v8
	global_load_dwordx4 v[24:27], v8, s[0:1] nt
	v_add_u32_e32 v8, s3, v8
	global_load_dwordx4 v[28:31], v8, s[0:1] nt
	v_add_u32_e32 v8, s3, v8
	global_load_dwordx4 v[32:35], v8, s[0:1] nt
	v_add_u32_e32 v8, s3, v8
	global_load_dwordx4 v[36:39], v8, s[0:1] nt
	v_add_u32_e32 v8, s3, v8
	global_load_dwordx4 v[40:43], v8, s[0:1] nt
	v_add_u32_e32 v8, s3, v8
	global_load_dwordx4 v[44:47], v8, s[0:1] nt
.Ltr_loop:
	s_add_i32 s35, s33, s34
	s_cmp_lt_i32 s35, 0xc000
	s_cbranch_scc0 .Ltr_last0
	s_mov_b32 s15, s35
	s_cmp_lt_u32 s15, 0x1800
	s_cbranch_scc1 .Ltr_a2
	s_sub_u32 s15, s15, 0x1800
	s_cmp_lt_u32 s15, 0x1800
	s_cbranch_scc1 .Ltr_b2
	s_sub_u32 s15, s15, 0x1800
	s_cmp_lt_u32 s15, 0x800
	s_cbranch_scc1 .Ltr_c2
	s_sub_u32 s15, s15, 0x800
	s_cmp_lt_u32 s15, 0x800
	s_cbranch_scc1 .Ltr_d2
	s_sub_u32 s15, s15, 0x800
	s_cmp_lt_u32 s15, 0x4000
	s_cbranch_scc1 .Ltr_e2
	s_sub_u32 s15, s15, 0x4000
	s_lshr_b32 s4, s15, 13
	s_and_b32 s15, s15, 0x1fff
	s_lshl_b32 s63, s4, 26
	s_add_u32 s0, s28, s63
	s_addc_u32 s1, s29, 0
	s_lshl_b32 s63, s4, 25
	s_add_u32 s64, s92, s63
	s_addc_u32 s65, s93, 0
	s_movk_i32 s5, 0x800
	s_movk_i32 s6, 0x2000
	s_mov_b32 s7, 0
	s_lshr_b32 s67, s15, 6
	s_and_b32 s68, s15, 63
	s_branch .Ltr_j2
.Ltr_a2:
	s_mov_b64 s[0:1], s[42:43]
	s_mov_b64 s[64:65], s[54:55]
	s_movk_i32 s5, 0x1800
	s_movk_i32 s6, 0x800
	s_mov_b32 s7, 1
	s_lshr_b32 s67, s15, 6
	s_mul_i32 s67, s67, 171
	s_lshr_b32 s67, s67, 9
	s_mul_i32 s68, s67, 192
	s_sub_u32 s68, s15, s68
	s_branch .Ltr_j2
.Ltr_b2:
	s_mov_b64 s[0:1], s[48:49]
	s_mov_b64 s[64:65], s[12:13]
	s_movk_i32 s5, 0x1800
	s_movk_i32 s6, 0x800
	s_mov_b32 s7, 0
	s_lshr_b32 s67, s15, 6
	s_mul_i32 s67, s67, 171
	s_lshr_b32 s67, s67, 9
	s_mul_i32 s68, s67, 192
	s_sub_u32 s68, s15, s68
	s_branch .Ltr_j2
.Ltr_c2:
	s_mov_b64 s[0:1], s[46:47]
	s_mov_b64 s[64:65], s[8:9]
	s_movk_i32 s5, 0x800
	s_movk_i32 s6, 0x800
	s_mov_b32 s7, 0
	s_lshr_b32 s67, s15, 6
	s_and_b32 s68, s15, 63
	s_branch .Ltr_j2
.Ltr_d2:
	s_mov_b64 s[0:1], s[24:25]
	s_mov_b64 s[64:65], s[58:59]
	s_movk_i32 s5, 0x800
	s_movk_i32 s6, 0x800
	s_mov_b32 s7, 0
	s_lshr_b32 s67, s15, 6
	s_and_b32 s68, s15, 63
	s_branch .Ltr_j2
.Ltr_e2:
	s_lshr_b32 s4, s15, 13
	s_and_b32 s15, s15, 0x1fff
	s_lshl_b32 s63, s4, 26
	s_add_u32 s0, s26, s63
	s_addc_u32 s1, s27, 0
	s_lshl_b32 s63, s4, 25
	s_add_u32 s64, s90, s63
	s_addc_u32 s65, s91, 0
	s_movk_i32 s5, 0x2000
	s_movk_i32 s6, 0x800
	s_mov_b32 s7, 0
	s_lshr_b32 s67, s15, 8
	s_and_b32 s68, s15, 0xff

; #define LAS __attribute__((address_space(3)))
; #define LDS_WAIT() asm volatile("s_waitcnt lgkmcnt(0)" ::: "memory")
; __device__ __forceinline__ unsigned pk2(float lo, float hi) { return f2bf(lo) | (f2bf(hi) << 16); }
; __device__ __forceinline__ void transpose_item(const float* W, int K, int N, bf16* WT, LAS float* scr, int item, int lane, bool bcu_map = false) {
;     const int nblk = N / 32, kb = item / nblk, nb = item % nblk, k0 = 64 * kb, n0 = 32 * nb;
; #pragma unroll 8
;     for (int i = 0; i < 32; ++i) { const int kk = 2 * i + (lane >> 5); scr[kk * 33 + (lane & 31)] = W[(size_t)(k0 + kk) * N + n0 + (lane & 31)]; }
;     LDS_WAIT(); asm volatile("" ::: "memory");
;     const int c = lane & 7;
; #pragma unroll
;     for (int j = 0; j < 4; ++j) { const int n = (lane >> 3) + 8 * j; const LAS float* s = scr + (8 * c) * 33 + n;
;         v4u o; o.x = pk2(s[0 * 33], s[1 * 33]); o.y = pk2(s[2 * 33], s[3 * 33]); o.z = pk2(s[4 * 33], s[5 * 33]); o.w = pk2(s[6 * 33], s[7 * 33]);
;         const int f_ = (n0 & 2047), row_ = !bcu_map ? n0 : (n0 < 2048 ? n0 : 2048 + (f_ >> 7) * 256 + (n0 >= 4096 ? 128 : 0) + (f_ & 127));
;         *(v4u*)(WT + (size_t)(row_ + n) * K + k0 + 8 * c) = o; }
.Ltr_r2:
	s_mul_i32 s63, s69, s6
	s_add_u32 s63, s63, s67
	s_lshl_b32 s63, s63, 1
	s_add_u32 s64, s64, s63
	s_addc_u32 s65, s65, 0
	s_lshl_b32 s66, s6, 1
	v_mul_u32_u24_e32 v10, s3, v1
	v_lshl_add_u32 v10, v2, 4, v10
	v_mul_u32_u24_e32 v11, s66, v3
	v_add_u32_e32 v11, v5, v11
	global_load_dwordx4 v[48:51], v10, s[0:1] nt
	v_add_u32_e32 v10, s3, v10
	global_load_dwordx4 v[52:55], v10, s[0:1] nt
	v_add_u32_e32 v10, s3, v10
	global_load_dwordx4 v[56:59], v10, s[0:1] nt
	v_add_u32_e32 v10, s3, v10
	global_load_dwordx4 v[60:63], v10, s[0:1] nt
	v_add_u32_e32 v10, s3, v10
	global_load_dwordx4 v[64:67], v10, s[0:1] nt
	v_add_u32_e32 v10, s3, v10
	global_load_dwordx4 v[68:71], v10, s[0:1] nt
	v_add_u32_e32 v10, s3, v10
	global_load_dwordx4 v[72:75], v10, s[0:1] nt
	v_add_u32_e32 v10, s3, v10
	global_load_dwordx4 v[76:79], v10, s[0:1] nt
	s_waitcnt vmcnt(8)
	v_cvt_pk_bf16_f32 v80, v16, v20
	v_cvt_pk_bf16_f32 v81, v24, v28
	v_cvt_pk_bf16_f32 v82, v32, v36
	v_cvt_pk_bf16_f32 v83, v40, v44
	v_cvt_pk_bf16_f32 v84, v17, v21
	v_cvt_pk_bf16_f32 v85, v25, v29
	v_cvt_pk_bf16_f32 v86, v33, v37
	v_cvt_pk_bf16_f32 v87, v41, v45
	v_cvt_pk_bf16_f32 v88, v18, v22
	v_cvt_pk_bf16_f32 v89, v26, v30
	v_cvt_pk_bf16_f32 v90, v34, v38
	v_cvt_pk_bf16_f32 v91, v42, v46
	v_cvt_pk_bf16_f32 v92, v19, v23
	v_cvt_pk_bf16_f32 v93, v27, v31
	v_cvt_pk_bf16_f32 v94, v35, v39
	v_cvt_pk_bf16_f32 v95, v43, v47
	global_store_dwordx4 v9, v[80:83], s[60:61]
	v_add_u32_e32 v9, s62, v9
	global_store_dwordx4 v9, v[84:87], s[60:61]
	v_add_u32_e32 v9, s62, v9
	global_store_dwordx4 v9, v[88:91], s[60:61]
	v_add_u32_e32 v9, s62, v9
	global_store_dwordx4 v9, v[92:95], s[60:61]
	s_add_i32 s33, s35, s34
	s_cmp_lt_i32 s33, 0xc000
	s_cbranch_scc0 .Ltr_last1
	s_mov_b32 s15, s33
	s_cmp_lt_u32 s15, 0x1800
	s_cbranch_scc1 .Ltr_a3
	s_sub_u32 s15, s15, 0x1800
	s_cmp_lt_u32 s15, 0x1800
	s_cbranch_scc1 .Ltr_b3
	s_sub_u32 s15, s15, 0x1800
	s_cmp_lt_u32 s15, 0x800
	s_cbranch_scc1 .Ltr_c3
	s_sub_u32 s15, s15, 0x800
	s_cmp_lt_u32 s15, 0x800
	s_cbranch_scc1 .Ltr_d3
	s_sub_u32 s15, s15, 0x800
	s_cmp_lt_u32 s15, 0x4000
	s_cbranch_scc1 .Ltr_e3
	s_sub_u32 s15, s15, 0x4000
	s_lshr_b32 s4, s15, 13
	s_and_b32 s15, s15, 0x1fff
	s_lshl_b32 s63, s4, 26
	s_add_u32 s0, s28, s63
	s_addc_u32 s1, s29, 0
	s_lshl_b32 s63, s4, 25
	s_add_u32 s60, s92, s63
	s_addc_u32 s61, s93, 0
	s_movk_i32 s5, 0x800
	s_movk_i32 s6, 0x2000
	s_mov_b32 s7, 0
	s_lshr_b32 s67, s15, 6
	s_and_b32 s68, s15, 63
	s_branch .Ltr_j3

; #define LAS __attribute__((address_space(3)))
; #define LDS_WAIT() asm volatile("s_waitcnt lgkmcnt(0)" ::: "memory")
; __device__ __forceinline__ unsigned pk2(float lo, float hi) { return f2bf(lo) | (f2bf(hi) << 16); }
; __device__ __forceinline__ void transpose_item(const float* W, int K, int N, bf16* WT, LAS float* scr, int item, int lane, bool bcu_map = false) {
;     const int nblk = N / 32, kb = item / nblk, nb = item % nblk, k0 = 64 * kb, n0 = 32 * nb;
; #pragma unroll 8
;     for (int i = 0; i < 32; ++i) { const int kk = 2 * i + (lane >> 5); scr[kk * 33 + (lane & 31)] = W[(size_t)(k0 + kk) * N + n0 + (lane & 31)]; }
;     LDS_WAIT(); asm volatile("" ::: "memory");
;     const int c = lane & 7;
; #pragma unroll
;     for (int j = 0; j < 4; ++j) { const int n = (lane >> 3) + 8 * j; const LAS float* s = scr + (8 * c) * 33 + n;
;         v4u o; o.x = pk2(s[0 * 33], s[1 * 33]); o.y = pk2(s[2 * 33], s[3 * 33]); o.z = pk2(s[4 * 33], s[5 * 33]); o.w = pk2(s[6 * 33], s[7 * 33]);
;         const int f_ = (n0 & 2047), row_ = !bcu_map ? n0 : (n0 < 2048 ? n0 : 2048 + (f_ >> 7) * 256 + (n0 >= 4096 ? 128 : 0) + (f_ & 127));
;         *(v4u*)(WT + (size_t)(row_ + n) * K + k0 + 8 * c) = o; }
;     LDS_WAIT(); asm volatile("" ::: "memory");
.Ltr_r3:
	s_mul_i32 s63, s69, s6
	s_add_u32 s63, s63, s67
	s_lshl_b32 s63, s63, 1
	s_add_u32 s60, s60, s63
	s_addc_u32 s61, s61, 0
	s_lshl_b32 s62, s6, 1
	v_mul_u32_u24_e32 v8, s3, v1
	v_lshl_add_u32 v8, v2, 4, v8
	v_mul_u32_u24_e32 v9, s62, v3
	v_add_u32_e32 v9, v5, v9
	global_load_dwordx4 v[16:19], v8, s[0:1] nt
	v_add_u32_e32 v8, s3, v8
	global_load_dwordx4 v[20:23], v8, s[0:1] nt
	v_add_u32_e32 v8, s3, v8
	global_load_dwordx4 v[24:27], v8, s[0:1] nt
	v_add_u32_e32 v8, s3, v8
	global_load_dwordx4 v[28:31], v8, s[0:1] nt
	v_add_u32_e32 v8, s3, v8
	global_load_dwordx4 v[32:35], v8, s[0:1] nt
	v_add_u32_e32 v8, s3, v8
	global_load_dwordx4 v[36:39], v8, s[0:1] nt
	v_add_u32_e32 v8, s3, v8
	global_load_dwordx4 v[40:43], v8, s[0:1] nt
	v_add_u32_e32 v8, s3, v8
	global_load_dwordx4 v[44:47], v8, s[0:1] nt
	s_waitcnt vmcnt(8)
	v_cvt_pk_bf16_f32 v80, v48, v52
	v_cvt_pk_bf16_f32 v81, v56, v60
	v_cvt_pk_bf16_f32 v82, v64, v68
	v_cvt_pk_bf16_f32 v83, v72, v76
	v_cvt_pk_bf16_f32 v84, v49, v53
	v_cvt_pk_bf16_f32 v85, v57, v61
	v_cvt_pk_bf16_f32 v86, v65, v69
	v_cvt_pk_bf16_f32 v87, v73, v77
	v_cvt_pk_bf16_f32 v88, v50, v54
	v_cvt_pk_bf16_f32 v89, v58, v62
	v_cvt_pk_bf16_f32 v90, v66, v70
	v_cvt_pk_bf16_f32 v91, v74, v78
	v_cvt_pk_bf16_f32 v92, v51, v55
	v_cvt_pk_bf16_f32 v93, v59, v63
	v_cvt_pk_bf16_f32 v94, v67, v71
	v_cvt_pk_bf16_f32 v95, v75, v79
	global_store_dwordx4 v11, v[80:83], s[64:65]
	v_add_u32_e32 v11, s66, v11
	global_store_dwordx4 v11, v[84:87], s[64:65]
	v_add_u32_e32 v11, s66, v11
	global_store_dwordx4 v11, v[88:91], s[64:65]
	v_add_u32_e32 v11, s66, v11
	global_store_dwordx4 v11, v[92:95], s[64:65]
	s_branch .Ltr_loop
.Ltr_last0:
	s_waitcnt vmcnt(0)
	v_cvt_pk_bf16_f32 v80, v16, v20
	v_cvt_pk_bf16_f32 v81, v24, v28
	v_cvt_pk_bf16_f32 v82, v32, v36
	v_cvt_pk_bf16_f32 v83, v40, v44
	v_cvt_pk_bf16_f32 v84, v17, v21
	v_cvt_pk_bf16_f32 v85, v25, v29
	v_cvt_pk_bf16_f32 v86, v33, v37
	v_cvt_pk_bf16_f32 v87, v41, v45
	v_cvt_pk_bf16_f32 v88, v18, v22
	v_cvt_pk_bf16_f32 v89, v26, v30
	v_cvt_pk_bf16_f32 v90, v34, v38
	v_cvt_pk_bf16_f32 v91, v42, v46
	v_cvt_pk_bf16_f32 v92, v19, v23
	v_cvt_pk_bf16_f32 v93, v27, v31
	v_cvt_pk_bf16_f32 v94, v35, v39
	v_cvt_pk_bf16_f32 v95, v43, v47
	global_store_dwordx4 v9, v[80:83], s[60:61]
	v_add_u32_e32 v9, s62, v9
	global_store_dwordx4 v9, v[84:87], s[60:61]
	v_add_u32_e32 v9, s62, v9
	global_store_dwordx4 v9, v[88:91], s[60:61]
	v_add_u32_e32 v9, s62, v9
	global_store_dwordx4 v9, v[92:95], s[60:61]
	s_branch .LBB0_40
.Ltr_last1:
	s_waitcnt vmcnt(0)
	v_cvt_pk_bf16_f32 v80, v48, v52
	v_cvt_pk_bf16_f32 v81, v56, v60
	v_cvt_pk_bf16_f32 v82, v64, v68
	v_cvt_pk_bf16_f32 v83, v72, v76
	v_cvt_pk_bf16_f32 v84, v49, v53
	v_cvt_pk_bf16_f32 v85, v57, v61
	v_cvt_pk_bf16_f32 v86, v65, v69
	v_cvt_pk_bf16_f32 v87, v73, v77
	v_cvt_pk_bf16_f32 v88, v50, v54
	v_cvt_pk_bf16_f32 v89, v58, v62
	v_cvt_pk_bf16_f32 v90, v66, v70
	v_cvt_pk_bf16_f32 v91, v74, v78
	v_cvt_pk_bf16_f32 v92, v51, v55
	v_cvt_pk_bf16_f32 v93, v59, v63
	v_cvt_pk_bf16_f32 v94, v67, v71
	v_cvt_pk_bf16_f32 v95, v75, v79
	global_store_dwordx4 v11, v[80:83], s[64:65]
	v_add_u32_e32 v11, s66, v11
	global_store_dwordx4 v11, v[84:87], s[64:65]
	v_add_u32_e32 v11, s66, v11
	global_store_dwordx4 v11, v[88:91], s[64:65]
	v_add_u32_e32 v11, s66, v11
	global_store_dwordx4 v11, v[92:95], s[64:65]
